# adds: phase0_rest weight stores write-through; P0 x-row loop waits only for loads (previous row stores stay in flight); HGRN full-pass loop-end drain only in the state-only path
# speedup vs baseline: 1.0028x; 1.0028x over previous
.LBB0_19:
	s_or_b64 exec, exec, s[2:3]
	v_lshlrev_b64 v[2:3], 13, v[2:3]
	v_lshl_add_u64 v[2:3], v[4:5], 0, v[2:3]
	v_mov_b32_e32 v35, 0
	v_lshlrev_b32_e32 v34, 4, v66
	v_lshl_add_u64 v[36:37], v[2:3], 0, v[34:35]
	v_add_co_u32_e32 v38, vcc, 0x1000, v36
	v_add_u32_e32 v34, 8, v74
	s_nop 0
	v_addc_co_u32_e32 v39, vcc, 0, v37, vcc
	global_load_dwordx4 v[30:33], v[38:39], off offset:3072 nt
	global_load_dwordx4 v[26:29], v[38:39], off offset:2048 nt
	global_load_dwordx4 v[22:25], v[38:39], off offset:1024 nt
	global_load_dwordx4 v[18:21], v[38:39], off nt
	global_load_dwordx4 v[14:17], v[36:37], off offset:3072 nt
	global_load_dwordx4 v[10:13], v[36:37], off offset:2048 nt
	global_load_dwordx4 v[6:9], v[36:37], off offset:1024 nt
	global_load_dwordx4 v[2:5], v[36:37], off nt
	v_lshlrev_b64 v[36:37], 12, v[68:69]
	v_lshl_or_b32 v36, v66, 3, v36
	v_lshl_add_u64 v[36:37], s[70:71], 0, v[36:37]
	s_mov_b64 s[2:3], 0x4200000
	s_ashr_i32 s69, s68, 31
	v_mul_lo_u32 v54, s90, v34
	v_lshl_add_u64 v[36:37], v[36:37], 0, s[2:3]
	s_lshl_b64 s[2:3], s[68:69], 12
	s_mov_b64 s[4:5], 0
	s_movk_i32 s12, 0x2440
	s_movk_i32 s13, 0x203f
	s_mov_b32 s14, 0xfe03f81
	v_lshlrev_b32_e32 v34, 4, v66
	s_movk_i32 s15, 0x243f
	v_readlane_b32 s16, v253, 0
	s_waitcnt vmcnt(0)
	s_branch .LBB0_23

.LBB0_23:
	s_nop 0
	v_add_u32_e32 v55, s16, v54
	v_cmp_gt_i32_e32 vcc, s12, v55
	s_waitcnt vmcnt(8)
	v_cvt_pk_bf16_f32 v38, v2, v3
	v_cvt_pk_bf16_f32 v39, v4, v5
	v_cvt_pk_bf16_f32 v40, v6, v7
	v_cvt_pk_bf16_f32 v41, v8, v9
	v_cvt_pk_bf16_f32 v42, v10, v11
	v_cvt_pk_bf16_f32 v43, v12, v13
	v_cvt_pk_bf16_f32 v44, v14, v15
	v_cvt_pk_bf16_f32 v45, v16, v17
	v_cvt_pk_bf16_f32 v46, v18, v19
	v_cvt_pk_bf16_f32 v47, v20, v21
	v_cvt_pk_bf16_f32 v48, v22, v23
	v_cvt_pk_bf16_f32 v49, v24, v25
	v_cvt_pk_bf16_f32 v50, v26, v27
	v_cvt_pk_bf16_f32 v51, v28, v29
	v_cvt_pk_bf16_f32 v52, v30, v31
	v_cvt_pk_bf16_f32 v53, v32, v33
	s_and_saveexec_b64 s[6:7], vcc
	s_cbranch_execz .LBB0_22
	v_cmp_lt_i32_e32 vcc, s13, v55
	s_and_saveexec_b64 s[10:11], vcc
	s_xor_b64 s[10:11], exec, s[10:11]
	v_add_u32_e32 v2, 0xffffdfc0, v55
	v_mov_b32_e32 v3, v35
	s_or_saveexec_b64 s[10:11], s[10:11]
	v_readlane_b32 s40, v253, 5
	v_readlane_b32 s42, v253, 7
	v_readlane_b32 s43, v253, 8
	v_readlane_b32 s41, v253, 6
	v_readlane_b32 s44, v253, 9
	v_mov_b64_e32 v[4:5], s[42:43]
	v_readlane_b32 s45, v253, 10
	v_readlane_b32 s46, v253, 11
	v_readlane_b32 s47, v253, 12
	v_readlane_b32 s48, v253, 13
	v_readlane_b32 s49, v253, 14
	v_readlane_b32 s50, v253, 15
	v_readlane_b32 s51, v253, 16
	v_readlane_b32 s52, v253, 17
	v_readlane_b32 s53, v253, 18
	v_readlane_b32 s54, v253, 19
	v_readlane_b32 s55, v253, 20
	s_xor_b64 exec, exec, s[10:11]
	s_cbranch_execz .LBB0_21
	v_mul_hi_i32 v2, v55, s14
	v_lshrrev_b32_e32 v3, 31, v2
	v_ashrrev_i32_e32 v2, 7, v2
	v_add_u32_e32 v6, v2, v3
	v_mul_i32_i24_e32 v2, 0xfffff7f0, v6
	v_readlane_b32 s40, v253, 5
	v_add3_u32 v2, v54, v2, s16
	v_readlane_b32 s50, v253, 15
	v_readlane_b32 s51, v253, 16
	v_cmp_lt_i32_e32 vcc, 15, v2
	v_readlane_b32 s41, v253, 6
	v_mov_b64_e32 v[4:5], s[50:51]
	v_readlane_b32 s42, v253, 7
	v_readlane_b32 s43, v253, 8
	v_readlane_b32 s44, v253, 9
	v_readlane_b32 s45, v253, 10
	v_readlane_b32 s46, v253, 11
	v_readlane_b32 s47, v253, 12
	v_readlane_b32 s48, v253, 13
	v_readlane_b32 s49, v253, 14
	v_readlane_b32 s52, v253, 17
	v_readlane_b32 s53, v253, 18
	v_readlane_b32 s54, v253, 19
	v_readlane_b32 s55, v253, 20
	s_and_saveexec_b64 s[18:19], vcc
	s_xor_b64 s[28:29], exec, s[18:19]
	s_cbranch_execz .LBB0_29
	v_ashrrev_i32_e32 v7, 31, v6
	v_readlane_b32 s40, v253, 5
	v_lshlrev_b64 v[4:5], 24, v[6:7]
	v_readlane_b32 s41, v253, 6
	v_add_u32_e32 v2, -16, v2
	v_mov_b32_e32 v3, v35
	v_readlane_b32 s42, v253, 7
	v_readlane_b32 s43, v253, 8
	v_readlane_b32 s44, v253, 9
	v_readlane_b32 s45, v253, 10
	v_readlane_b32 s46, v253, 11
	v_readlane_b32 s47, v253, 12
	v_readlane_b32 s48, v253, 13
	v_readlane_b32 s49, v253, 14
	v_readlane_b32 s50, v253, 15
	v_readlane_b32 s51, v253, 16
	v_readlane_b32 s52, v253, 17
	v_readlane_b32 s53, v253, 18
	v_readlane_b32 s54, v253, 19
	v_readlane_b32 s55, v253, 20
	v_lshl_add_u64 v[4:5], s[40:41], 0, v[4:5]

.LBB0_239:
	s_or_b64 exec, exec, s[30:31]
	v_lshrrev_b32_e32 v81, 5, v81
	v_cvt_f32_u32_e32 v84, v81
	ds_write2_b32 v80, v46, v47 offset1:1
	v_add_u32_e32 v47, 0x420, v80
	ds_write2_b32 v47, v34, v35 offset1:1
	v_rcp_iflag_f32_e32 v46, v84
	v_add_u32_e32 v35, 0x840, v80
	ds_write2_b32 v35, v30, v31 offset1:1
	v_add_u32_e32 v30, 0x848, v80
	ds_write2_b32 v30, v32, v33 offset1:1
	v_add_u32_e32 v30, 0xc60, v80
	ds_write2_b32 v30, v26, v27 offset1:1
	v_add_u32_e32 v26, 0xc68, v80
	v_mul_f32_e32 v46, 0x4f7ffffe, v46
	ds_write2_b32 v26, v28, v29 offset1:1
	v_add_u32_e32 v26, 0x1080, v80
	v_cvt_u32_f32_e32 v46, v46
	ds_write2_b32 v26, v22, v23 offset1:1
	v_add_u32_e32 v22, 0x1088, v80
	ds_write2_b32 v22, v24, v25 offset1:1
	v_add_u32_e32 v22, 0x14a0, v80
	ds_write2_b32 v22, v10, v11 offset1:1
	v_add_u32_e32 v10, 0x14a8, v80
	v_sub_u32_e32 v84, 0, v81
	ds_write2_b32 v10, v12, v13 offset1:1
	v_add_u32_e32 v10, 0x18c0, v80
	v_mul_lo_u32 v34, v84, v46
	ds_write2_b32 v10, v6, v7 offset1:1
	v_add_u32_e32 v6, 0x18c8, v80
	v_sub_u32_e32 v86, 0, v71
	v_mul_hi_u32 v34, v46, v34
	ds_write2_b32 v6, v8, v9 offset1:1
	v_add_u32_e32 v6, 0x1ce0, v80
	ds_write2_b32 v80, v48, v49 offset0:2 offset1:3
	v_add_u32_e32 v48, 0x428, v80
	v_max_i32_e32 v49, v71, v86
	v_add_u32_e32 v34, v46, v34
	ds_write2_b32 v6, v2, v3 offset1:1
	v_add_u32_e32 v2, 0x1ce8, v80
	ds_write2_b32 v48, v36, v37 offset1:1
	ds_write2_b32 v2, v4, v5 offset1:1
	v_mul_hi_u32 v6, v49, v34
	s_waitcnt lgkmcnt(0)
	v_mul_lo_u32 v4, v6, v81
	ds_read2_b32 v[2:3], v78 offset1:33
	v_sub_u32_e32 v7, v49, v4
	v_add_u32_e32 v8, 1, v6
	s_waitcnt lgkmcnt(0)
	v_cvt_pk_bf16_f32 v2, v2, v3
	v_cmp_ge_u32_e32 vcc, v7, v81
	v_sub_u32_e32 v3, v7, v81
	v_ashrrev_i32_e32 v85, 31, v71
	v_cndmask_b32_e32 v6, v6, v8, vcc
	v_cndmask_b32_e32 v7, v7, v3, vcc
	v_add_u32_e32 v8, 1, v6
	v_cmp_ge_u32_e32 vcc, v7, v81
	ds_read2_b32 v[4:5], v78 offset0:66 offset1:99
	s_waitcnt lgkmcnt(0)
	v_cvt_pk_bf16_f32 v3, v4, v5
	ds_read2_b32 v[4:5], v78 offset0:132 offset1:165
	v_cndmask_b32_e32 v6, v6, v8, vcc
	v_xor_b32_e32 v6, v6, v85
	v_sub_u32_e32 v7, v6, v85
	s_waitcnt lgkmcnt(0)
	v_cvt_pk_bf16_f32 v4, v4, v5
	v_mul_lo_u32 v5, v7, v81
	v_sub_u32_e32 v5, v71, v5
	ds_read2_b32 v[8:9], v78 offset0:198 offset1:231
	v_lshlrev_b32_e32 v12, 5, v5
	s_waitcnt lgkmcnt(0)
	v_cvt_pk_bf16_f32 v5, v8, v9
	v_or_b32_e32 v8, v12, v74
	v_lshlrev_b32_e32 v6, 6, v7
	v_ashrrev_i32_e32 v9, 31, v8
	v_ashrrev_i32_e32 v7, 31, v6
	v_lshlrev_b64 v[8:9], 12, v[8:9]
	v_lshl_add_u64 v[8:9], v[66:67], 0, v[8:9]
	v_lshlrev_b64 v[6:7], 1, v[6:7]
	v_lshl_add_u64 v[8:9], v[8:9], 0, v[6:7]
	v_mov_b32_e32 v71, v69
	v_lshl_add_u64 v[8:9], v[8:9], 0, v[70:71]
	ds_read2_b32 v[10:11], v78 offset0:8 offset1:41
	global_store_dwordx4 v[8:9], v[2:5], off sc0 sc1
	v_add_u32_e32 v79, s12, v79
	s_waitcnt vmcnt(4)
	v_mov_b64_e32 v[22:23], v[50:51]
	s_waitcnt lgkmcnt(0)
	v_cvt_pk_bf16_f32 v2, v10, v11
	ds_read2_b32 v[4:5], v78 offset0:74 offset1:107
	s_waitcnt lgkmcnt(0)
	v_cvt_pk_bf16_f32 v3, v4, v5
	ds_read2_b32 v[4:5], v78 offset0:140 offset1:173
	s_waitcnt lgkmcnt(0)
	v_cvt_pk_bf16_f32 v4, v4, v5
	ds_read2_b32 v[8:9], v78 offset0:206 offset1:239
	s_waitcnt lgkmcnt(0)
	v_cvt_pk_bf16_f32 v5, v8, v9
	v_or_b32_e32 v8, v12, v75
	v_ashrrev_i32_e32 v9, 31, v8
	v_lshlrev_b64 v[8:9], 12, v[8:9]
	v_lshl_add_u64 v[8:9], v[66:67], 0, v[8:9]
	v_lshl_add_u64 v[8:9], v[8:9], 0, v[6:7]
	v_lshl_add_u64 v[8:9], v[8:9], 0, v[70:71]
	ds_read2_b32 v[10:11], v78 offset0:16 offset1:49
	global_store_dwordx4 v[8:9], v[2:5], off sc0 sc1
	v_mov_b64_e32 v[26:27], v[42:43]
	v_mov_b64_e32 v[30:31], v[38:39]
	s_waitcnt lgkmcnt(0)
	v_cvt_pk_bf16_f32 v2, v10, v11
	ds_read2_b32 v[4:5], v78 offset0:82 offset1:115
	s_waitcnt lgkmcnt(0)
	v_cvt_pk_bf16_f32 v3, v4, v5
	ds_read2_b32 v[4:5], v78 offset0:148 offset1:181
	s_waitcnt lgkmcnt(0)
	v_cvt_pk_bf16_f32 v4, v4, v5
	ds_read2_b32 v[8:9], v78 offset0:214 offset1:247
	s_waitcnt lgkmcnt(0)
	v_cvt_pk_bf16_f32 v5, v8, v9
	v_or_b32_e32 v8, v12, v76
	v_ashrrev_i32_e32 v9, 31, v8
	v_lshlrev_b64 v[8:9], 12, v[8:9]
	v_lshl_add_u64 v[8:9], v[66:67], 0, v[8:9]
	v_lshl_add_u64 v[8:9], v[8:9], 0, v[6:7]
	v_lshl_add_u64 v[8:9], v[8:9], 0, v[70:71]
	ds_read2_b32 v[10:11], v78 offset0:24 offset1:57
	global_store_dwordx4 v[8:9], v[2:5], off sc0 sc1
	v_mov_b64_e32 v[36:37], v[20:21]
	v_mov_b64_e32 v[48:49], v[16:17]
	s_waitcnt lgkmcnt(0)
	v_cvt_pk_bf16_f32 v2, v10, v11
	ds_read2_b32 v[4:5], v78 offset0:90 offset1:123
	s_waitcnt lgkmcnt(0)
	v_cvt_pk_bf16_f32 v3, v4, v5
	ds_read2_b32 v[4:5], v78 offset0:156 offset1:189
	s_waitcnt lgkmcnt(0)
	v_cvt_pk_bf16_f32 v4, v4, v5
	ds_read2_b32 v[8:9], v78 offset0:222 offset1:255
	s_waitcnt lgkmcnt(0)
	v_cvt_pk_bf16_f32 v5, v8, v9
	v_or_b32_e32 v8, v12, v77
	v_ashrrev_i32_e32 v9, 31, v8
	v_lshlrev_b64 v[8:9], 12, v[8:9]
	v_lshl_add_u64 v[8:9], v[66:67], 0, v[8:9]
	v_lshl_add_u64 v[6:7], v[8:9], 0, v[6:7]
	v_lshl_add_u64 v[6:7], v[6:7], 0, v[70:71]
	global_store_dwordx4 v[6:7], v[2:5], off sc0 sc1
	s_waitcnt lgkmcnt(0)
	s_waitcnt vmcnt(5)
	v_mov_b64_e32 v[6:7], v[58:59]
	v_mov_b64_e32 v[10:11], v[54:55]
	v_add_u32_e32 v2, s14, v79
	v_cmp_lt_i32_e32 vcc, s18, v2
	s_waitcnt vmcnt(4)
	v_mov_b64_e32 v[2:3], v[62:63]
	s_or_b64 s[10:11], vcc, s[10:11]
	v_mov_b64_e32 v[4:5], v[64:65]
	v_mov_b64_e32 v[8:9], v[60:61]
	v_mov_b64_e32 v[12:13], v[56:57]
	v_mov_b64_e32 v[24:25], v[52:53]
	v_mov_b64_e32 v[28:29], v[44:45]
	v_mov_b64_e32 v[32:33], v[40:41]
	v_mov_b64_e32 v[34:35], v[18:19]
	v_mov_b64_e32 v[46:47], v[14:15]
	v_mov_b32_e32 v71, v82
	v_mov_b64_e32 v[66:67], v[72:73]
	v_mov_b32_e32 v81, v83
	s_andn2_b64 exec, exec, s[10:11]
	s_cbranch_execz .LBB0_246

.LBB0_432:
	s_and_b64 vcc, exec, s[10:11]
	s_cbranch_vccz .LBB0_434
	v_add_u32_e32 v42, v167, v165
	v_add_u32_e32 v43, v166, v176
	ds_read_b128 v[34:37], v42 offset:34816
	ds_read_b128 v[44:47], v43 offset:53248
	ds_read_b128 v[48:51], v43 offset:55552
	ds_read_b128 v[52:55], v43 offset:57856
	ds_read_b128 v[56:59], v43 offset:60160
	ds_read_b128 v[60:63], v43 offset:62464
	ds_read_b128 v[126:129], v43 offset:64768
	ds_read_b128 v[130:133], v191 offset:13824
	ds_read_b128 v[134:137], v191 offset:16128
	ds_read_b128 v[38:41], v42 offset:34880
	s_waitcnt lgkmcnt(8)
	v_mfma_f32_16x16x32_bf16 v[2:5], v[34:37], v[44:47], v[2:5]
	ds_read_b128 v[44:47], v43 offset:53312
	s_waitcnt lgkmcnt(8)
	v_mfma_f32_16x16x32_bf16 v[6:9], v[34:37], v[48:51], v[6:9]
	ds_read_b128 v[48:51], v43 offset:55616
	s_waitcnt lgkmcnt(8)
	v_mfma_f32_16x16x32_bf16 v[10:13], v[34:37], v[52:55], v[10:13]
	ds_read_b128 v[52:55], v43 offset:57920
	s_waitcnt lgkmcnt(8)
	v_mfma_f32_16x16x32_bf16 v[14:17], v[34:37], v[56:59], v[14:17]
	ds_read_b128 v[56:59], v43 offset:60224
	s_waitcnt lgkmcnt(8)
	v_mfma_f32_16x16x32_bf16 v[18:21], v[34:37], v[60:63], v[18:21]
	ds_read_b128 v[60:63], v43 offset:62528
	s_waitcnt lgkmcnt(8)
	v_mfma_f32_16x16x32_bf16 v[22:25], v[34:37], v[126:129], v[22:25]
	ds_read_b128 v[126:129], v43 offset:64832
	s_waitcnt lgkmcnt(8)
	v_mfma_f32_16x16x32_bf16 v[26:29], v[34:37], v[130:133], v[26:29]
	ds_read_b128 v[130:133], v192 offset:13824
	s_waitcnt lgkmcnt(8)
	v_mfma_f32_16x16x32_bf16 v[30:33], v[34:37], v[134:137], v[30:33]
	ds_read_b128 v[134:137], v192 offset:16128
	s_waitcnt lgkmcnt(7)
	v_mfma_f32_16x16x32_bf16 v[2:5], v[38:41], v[44:47], v[2:5]
	s_waitcnt lgkmcnt(6)
	v_mfma_f32_16x16x32_bf16 v[6:9], v[38:41], v[48:51], v[6:9]
	s_waitcnt lgkmcnt(5)
	v_mfma_f32_16x16x32_bf16 v[10:13], v[38:41], v[52:55], v[10:13]
	s_waitcnt lgkmcnt(4)
	v_mfma_f32_16x16x32_bf16 v[14:17], v[38:41], v[56:59], v[14:17]
	s_waitcnt lgkmcnt(3)
	v_mfma_f32_16x16x32_bf16 v[18:21], v[38:41], v[60:63], v[18:21]
	s_waitcnt lgkmcnt(2)
	v_mfma_f32_16x16x32_bf16 v[22:25], v[38:41], v[126:129], v[22:25]
	s_waitcnt lgkmcnt(1)
	v_mfma_f32_16x16x32_bf16 v[26:29], v[38:41], v[130:133], v[26:29]
	s_waitcnt lgkmcnt(0)
	v_mfma_f32_16x16x32_bf16 v[30:33], v[38:41], v[134:137], v[30:33]
	v_pk_mul_f32 v[34:35], v[122:123], v[2:3]
	v_mul_f32_e64 v36, v124, v4
	v_mul_f32_e64 v37, v125, v5
	v_pk_mul_f32 v[38:39], v[122:123], v[6:7]
	v_pk_mul_f32 v[40:41], v[124:125], v[8:9]
	v_pk_mul_f32 v[42:43], v[122:123], v[10:11]
	v_pk_mul_f32 v[44:45], v[124:125], v[12:13]
	v_pk_mul_f32 v[46:47], v[122:123], v[14:15]
	v_pk_mul_f32 v[48:49], v[124:125], v[16:17]
	v_pk_mul_f32 v[50:51], v[122:123], v[18:19]
	v_pk_mul_f32 v[52:53], v[124:125], v[20:21]
	v_pk_mul_f32 v[54:55], v[122:123], v[22:23]
	v_pk_mul_f32 v[56:57], v[124:125], v[24:25]
	v_pk_mul_f32 v[58:59], v[122:123], v[26:27]
	v_pk_mul_f32 v[60:61], v[124:125], v[28:29]
	v_pk_mul_f32 v[62:63], v[122:123], v[30:31]
	v_pk_mul_f32 v[64:65], v[124:125], v[32:33]
	s_waitcnt vmcnt(0)
.LBB0_434:
	s_mov_b64 vcc, s[90:91]
	v_lshlrev_b32_e32 v3, 16, v241
	v_cndmask_b32_sdwa v2, v147, v240, vcc dst_sel:DWORD dst_unused:UNUSED_PAD src0_sel:DWORD src1_sel:WORD_0
	v_cndmask_b32_e64 v3, 0, v3, s[92:93]
	v_or_b32_e32 v121, v3, v2
	v_and_b32_e32 v2, 0xffff, v234
	v_lshlrev_b32_e32 v3, 16, v236
	v_cndmask_b32_e64 v2, 0, v2, s[86:87]
	v_cndmask_b32_e64 v3, 0, v3, s[88:89]
	v_or_b32_e32 v120, v3, v2
	v_and_b32_e32 v2, 0xffff, v228
	v_lshlrev_b32_e32 v3, 16, v230
	v_cndmask_b32_e64 v2, 0, v2, s[82:83]
	v_cndmask_b32_e64 v3, 0, v3, s[84:85]
	v_or_b32_e32 v119, v3, v2
	v_and_b32_e32 v2, 0xffff, v222
	v_lshlrev_b32_e32 v3, 16, v224
	v_cndmask_b32_e64 v2, 0, v2, s[78:79]
	v_cndmask_b32_e64 v3, 0, v3, s[80:81]
	v_or_b32_e32 v118, v3, v2
	v_and_b32_e32 v2, 0xffff, v216
	v_lshlrev_b32_e32 v3, 16, v218
	v_cndmask_b32_e64 v2, 0, v2, s[74:75]
	v_cndmask_b32_e64 v3, 0, v3, s[76:77]
	s_waitcnt lgkmcnt(0)
	v_pk_mul_f32 v[116:117], v[116:117], v[124:125]
	v_or_b32_e32 v125, v3, v2
	v_and_b32_e32 v2, 0xffff, v210
	v_lshlrev_b32_e32 v3, 16, v212
	v_cndmask_b32_e64 v2, 0, v2, s[70:71]
	v_cndmask_b32_e64 v3, 0, v3, s[72:73]
	v_or_b32_e32 v124, v3, v2
	v_and_b32_e32 v2, 0xffff, v204
	v_lshlrev_b32_e32 v3, 16, v206
	v_cndmask_b32_e64 v2, 0, v2, s[66:67]
	v_cndmask_b32_e64 v3, 0, v3, s[68:69]
	v_pk_mul_f32 v[114:115], v[114:115], v[122:123]
	v_or_b32_e32 v123, v3, v2
	v_and_b32_e32 v2, 0xffff, v198
	v_lshlrev_b32_e32 v3, 16, v200
	v_cndmask_b32_e64 v2, 0, v2, s[62:63]
	v_cndmask_b32_e64 v3, 0, v3, s[64:65]
	v_cndmask_b32_e64 v240, 1.0, v242, s[92:93]
	v_cndmask_b32_e64 v153, 0, v239, s[92:93]
	v_cndmask_b32_e64 v127, 1.0, v238, s[90:91]
	v_cndmask_b32_e64 v126, 0, v237, s[90:91]
	v_cndmask_b32_e64 v130, 1.0, v235, s[88:89]
	v_cndmask_b32_e64 v128, 0, v232, s[88:89]
	v_cndmask_b32_e64 v131, 1.0, v233, s[86:87]
	v_cndmask_b32_e64 v129, 0, v231, s[86:87]
	v_cndmask_b32_e64 v134, 1.0, v229, s[84:85]
	v_cndmask_b32_e64 v132, 0, v226, s[84:85]
	v_cndmask_b32_e64 v135, 1.0, v227, s[82:83]
	v_cndmask_b32_e64 v133, 0, v225, s[82:83]
	v_cndmask_b32_e64 v138, 1.0, v223, s[80:81]
	v_cndmask_b32_e64 v136, 0, v220, s[80:81]
	v_cndmask_b32_e64 v139, 1.0, v221, s[78:79]
	v_cndmask_b32_e64 v137, 0, v219, s[78:79]
	v_cndmask_b32_e64 v142, 1.0, v217, s[76:77]
	v_cndmask_b32_e64 v140, 0, v214, s[76:77]
	v_cndmask_b32_e64 v143, 1.0, v215, s[74:75]
	v_cndmask_b32_e64 v141, 0, v213, s[74:75]
	v_cndmask_b32_e64 v152, 1.0, v211, s[72:73]
	v_cndmask_b32_e64 v144, 0, v208, s[72:73]
	v_cndmask_b32_e64 v208, 1.0, v209, s[70:71]
	v_cndmask_b32_e64 v145, 0, v207, s[70:71]
	v_cndmask_b32_e64 v204, 1.0, v205, s[68:69]
	v_cndmask_b32_e64 v202, 0, v202, s[68:69]
	v_cndmask_b32_e64 v203, 1.0, v203, s[66:67]
	v_cndmask_b32_e64 v201, 0, v201, s[66:67]
	v_cndmask_b32_e64 v198, 1.0, v199, s[64:65]
	v_cndmask_b32_e64 v196, 0, v196, s[64:65]
	v_or_b32_e32 v122, v3, v2
	v_cndmask_b32_e64 v197, 1.0, v197, s[62:63]
	v_cndmask_b32_e64 v195, 0, v195, s[62:63]
	s_and_b64 vcc, exec, s[0:1]
	s_cbranch_vccnz .LBB0_437
	v_mov_b64_e32 v[2:3], v[34:35]
	s_mov_b32 s24, s12
	v_mov_b64_e32 v[4:5], v[36:37]
	v_mov_b64_e32 v[6:7], v[38:39]
	v_mov_b64_e32 v[8:9], v[40:41]
	v_mov_b64_e32 v[10:11], v[42:43]
	v_mov_b64_e32 v[12:13], v[44:45]
	v_mov_b64_e32 v[14:15], v[46:47]
	v_mov_b64_e32 v[16:17], v[48:49]
	v_mov_b64_e32 v[18:19], v[50:51]
	v_mov_b64_e32 v[20:21], v[52:53]
	v_mov_b64_e32 v[22:23], v[54:55]
	v_mov_b64_e32 v[24:25], v[56:57]
	v_mov_b64_e32 v[26:27], v[58:59]
	v_mov_b64_e32 v[28:29], v[60:61]
	v_mov_b64_e32 v[30:31], v[62:63]
	v_mov_b64_e32 v[32:33], v[64:65]
	s_branch .LBB0_372
